# v20 + P6 sample-row slab summation as a rolling 8-deep load pipeline (was 8 serial load/wait rounds)
# speedup vs baseline: 1.0010x; 1.0010x over previous
.LBB0_2373:
	v_lshl_add_u64 v[128:129], s[46:47], 0, v[192:193]
	v_add_co_u32_e32 v138, vcc, 0x10400000, v128
	s_nop 1
	v_addc_co_u32_e32 v139, vcc, 0, v129, vcc
	v_add_co_u32_e32 v140, vcc, 0x10800000, v128
	s_nop 1
	v_addc_co_u32_e32 v141, vcc, 0, v129, vcc
	v_add_co_u32_e32 v142, vcc, 0x10c00000, v128
	s_nop 1
	v_addc_co_u32_e32 v143, vcc, 0, v129, vcc
	v_add_co_u32_e32 v144, vcc, 0x11000000, v128
	s_nop 1
	v_addc_co_u32_e32 v145, vcc, 0, v129, vcc
	v_add_co_u32_e32 v136, vcc, 0x11400000, v128
	s_nop 1
	v_addc_co_u32_e32 v137, vcc, 0, v129, vcc
	v_add_co_u32_e32 v130, vcc, 0x11800000, v128
	s_nop 1
	v_addc_co_u32_e32 v131, vcc, 0, v129, vcc
	v_add_co_u32_e32 v132, vcc, 0x11c00000, v128
	s_nop 1
	v_addc_co_u32_e32 v133, vcc, 0, v129, vcc
	v_add_co_u32_e32 v134, vcc, 0x12000000, v128
	s_nop 1
	v_addc_co_u32_e32 v135, vcc, 0, v129, vcc
	global_load_dwordx4 v[146:149], v[138:139], off
	global_load_dwordx4 v[150:153], v[140:141], off
	global_load_dwordx4 v[154:157], v[142:143], off
	global_load_dwordx4 v[206:209], v[144:145], off
	global_load_dwordx4 v[210:213], v[136:137], off
	global_load_dwordx4 v[214:217], v[130:131], off
	global_load_dwordx4 v[218:221], v[132:133], off
	global_load_dwordx4 v[222:225], v[134:135], off
	v_add_co_u32_e32 v226, vcc, 0x10401000, v128
	s_nop 1
	v_addc_co_u32_e32 v227, vcc, 0, v129, vcc
	v_add_co_u32_e32 v228, vcc, 0x10801000, v128
	s_nop 1
	v_addc_co_u32_e32 v229, vcc, 0, v129, vcc
	v_add_co_u32_e32 v230, vcc, 0x10c01000, v128
	s_nop 1
	v_addc_co_u32_e32 v231, vcc, 0, v129, vcc
	v_add_co_u32_e32 v232, vcc, 0x11001000, v128
	s_nop 1
	v_addc_co_u32_e32 v233, vcc, 0, v129, vcc
	v_add_co_u32_e32 v234, vcc, 0x11401000, v128
	s_nop 1
	v_addc_co_u32_e32 v235, vcc, 0, v129, vcc
	v_add_co_u32_e32 v236, vcc, 0x11801000, v128
	s_nop 1
	v_addc_co_u32_e32 v237, vcc, 0, v129, vcc
	v_add_co_u32_e32 v238, vcc, 0x11c01000, v128
	s_nop 1
	v_addc_co_u32_e32 v239, vcc, 0, v129, vcc
	v_add_co_u32_e32 v240, vcc, 0x12001000, v128
	s_nop 1
	v_addc_co_u32_e32 v241, vcc, 0, v129, vcc
	s_waitcnt vmcnt(7)
	v_pk_add_f32 v[30:31], v[148:149], v[30:31]
	v_pk_add_f32 v[28:29], v[146:147], v[28:29]
	global_load_dwordx4 v[146:149], v[138:139], off offset:1024
	s_waitcnt vmcnt(7)
	v_pk_add_f32 v[30:31], v[152:153], v[30:31]
	v_pk_add_f32 v[28:29], v[150:151], v[28:29]
	global_load_dwordx4 v[150:153], v[140:141], off offset:1024
	s_waitcnt vmcnt(7)
	v_pk_add_f32 v[30:31], v[156:157], v[30:31]
	v_pk_add_f32 v[28:29], v[154:155], v[28:29]
	global_load_dwordx4 v[154:157], v[142:143], off offset:1024
	s_waitcnt vmcnt(7)
	v_pk_add_f32 v[30:31], v[208:209], v[30:31]
	v_pk_add_f32 v[28:29], v[206:207], v[28:29]
	global_load_dwordx4 v[206:209], v[144:145], off offset:1024
	s_waitcnt vmcnt(7)
	v_pk_add_f32 v[30:31], v[212:213], v[30:31]
	v_pk_add_f32 v[28:29], v[210:211], v[28:29]
	global_load_dwordx4 v[210:213], v[136:137], off offset:1024
	s_waitcnt vmcnt(7)
	v_pk_add_f32 v[30:31], v[216:217], v[30:31]
	v_pk_add_f32 v[28:29], v[214:215], v[28:29]
	global_load_dwordx4 v[214:217], v[130:131], off offset:1024
	s_waitcnt vmcnt(7)
	v_pk_add_f32 v[30:31], v[220:221], v[30:31]
	v_pk_add_f32 v[28:29], v[218:219], v[28:29]
	global_load_dwordx4 v[218:221], v[132:133], off offset:1024
	s_waitcnt vmcnt(7)
	v_pk_add_f32 v[30:31], v[224:225], v[30:31]
	v_pk_add_f32 v[28:29], v[222:223], v[28:29]
	global_load_dwordx4 v[222:225], v[134:135], off offset:1024
	s_waitcnt vmcnt(7)
	v_pk_add_f32 v[26:27], v[148:149], v[26:27]
	v_pk_add_f32 v[24:25], v[146:147], v[24:25]
	global_load_dwordx4 v[146:149], v[138:139], off offset:2048
	s_waitcnt vmcnt(7)
	v_pk_add_f32 v[26:27], v[152:153], v[26:27]
	v_pk_add_f32 v[24:25], v[150:151], v[24:25]
	global_load_dwordx4 v[150:153], v[140:141], off offset:2048
	s_waitcnt vmcnt(7)
	v_pk_add_f32 v[26:27], v[156:157], v[26:27]
	v_pk_add_f32 v[24:25], v[154:155], v[24:25]
	global_load_dwordx4 v[154:157], v[142:143], off offset:2048
	s_waitcnt vmcnt(7)
	v_pk_add_f32 v[26:27], v[208:209], v[26:27]
	v_pk_add_f32 v[24:25], v[206:207], v[24:25]
	global_load_dwordx4 v[206:209], v[144:145], off offset:2048
	s_waitcnt vmcnt(7)
	v_pk_add_f32 v[26:27], v[212:213], v[26:27]
	v_pk_add_f32 v[24:25], v[210:211], v[24:25]
	global_load_dwordx4 v[210:213], v[136:137], off offset:2048
	s_waitcnt vmcnt(7)
	v_pk_add_f32 v[26:27], v[216:217], v[26:27]
	v_pk_add_f32 v[24:25], v[214:215], v[24:25]
	global_load_dwordx4 v[214:217], v[130:131], off offset:2048
	s_waitcnt vmcnt(7)
	v_pk_add_f32 v[26:27], v[220:221], v[26:27]
	v_pk_add_f32 v[24:25], v[218:219], v[24:25]
	global_load_dwordx4 v[218:221], v[132:133], off offset:2048
	s_waitcnt vmcnt(7)
	v_pk_add_f32 v[26:27], v[224:225], v[26:27]
	v_pk_add_f32 v[24:25], v[222:223], v[24:25]
	global_load_dwordx4 v[222:225], v[134:135], off offset:2048
	s_waitcnt vmcnt(7)
	v_pk_add_f32 v[22:23], v[148:149], v[22:23]
	v_pk_add_f32 v[20:21], v[146:147], v[20:21]
	global_load_dwordx4 v[146:149], v[138:139], off offset:3072
	s_waitcnt vmcnt(7)
	v_pk_add_f32 v[22:23], v[152:153], v[22:23]
	v_pk_add_f32 v[20:21], v[150:151], v[20:21]
	global_load_dwordx4 v[150:153], v[140:141], off offset:3072
	s_waitcnt vmcnt(7)
	v_pk_add_f32 v[22:23], v[156:157], v[22:23]
	v_pk_add_f32 v[20:21], v[154:155], v[20:21]
	global_load_dwordx4 v[154:157], v[142:143], off offset:3072
	s_waitcnt vmcnt(7)
	v_pk_add_f32 v[22:23], v[208:209], v[22:23]
	v_pk_add_f32 v[20:21], v[206:207], v[20:21]
	global_load_dwordx4 v[206:209], v[144:145], off offset:3072
	s_waitcnt vmcnt(7)
	v_pk_add_f32 v[22:23], v[212:213], v[22:23]
	v_pk_add_f32 v[20:21], v[210:211], v[20:21]
	global_load_dwordx4 v[210:213], v[136:137], off offset:3072
	s_waitcnt vmcnt(7)
	v_pk_add_f32 v[22:23], v[216:217], v[22:23]
	v_pk_add_f32 v[20:21], v[214:215], v[20:21]
	global_load_dwordx4 v[214:217], v[130:131], off offset:3072
	s_waitcnt vmcnt(7)
	v_pk_add_f32 v[22:23], v[220:221], v[22:23]
	v_pk_add_f32 v[20:21], v[218:219], v[20:21]
	global_load_dwordx4 v[218:221], v[132:133], off offset:3072
	s_waitcnt vmcnt(7)
	v_pk_add_f32 v[22:23], v[224:225], v[22:23]
	v_pk_add_f32 v[20:21], v[222:223], v[20:21]
	global_load_dwordx4 v[222:225], v[134:135], off offset:3072
	s_waitcnt vmcnt(7)
	v_pk_add_f32 v[18:19], v[148:149], v[18:19]
	v_pk_add_f32 v[16:17], v[146:147], v[16:17]
	global_load_dwordx4 v[146:149], v[226:227], off
	s_waitcnt vmcnt(7)
	v_pk_add_f32 v[18:19], v[152:153], v[18:19]
	v_pk_add_f32 v[16:17], v[150:151], v[16:17]
	global_load_dwordx4 v[150:153], v[228:229], off
	s_waitcnt vmcnt(7)
	v_pk_add_f32 v[18:19], v[156:157], v[18:19]
	v_pk_add_f32 v[16:17], v[154:155], v[16:17]
	global_load_dwordx4 v[154:157], v[230:231], off
	s_waitcnt vmcnt(7)
	v_pk_add_f32 v[18:19], v[208:209], v[18:19]
	v_pk_add_f32 v[16:17], v[206:207], v[16:17]
	global_load_dwordx4 v[206:209], v[232:233], off
	s_waitcnt vmcnt(7)
	v_pk_add_f32 v[18:19], v[212:213], v[18:19]
	v_pk_add_f32 v[16:17], v[210:211], v[16:17]
	global_load_dwordx4 v[210:213], v[234:235], off
	s_waitcnt vmcnt(7)
	v_pk_add_f32 v[18:19], v[216:217], v[18:19]
	v_pk_add_f32 v[16:17], v[214:215], v[16:17]
	global_load_dwordx4 v[214:217], v[236:237], off
	s_waitcnt vmcnt(7)
	v_pk_add_f32 v[18:19], v[220:221], v[18:19]
	v_pk_add_f32 v[16:17], v[218:219], v[16:17]
	global_load_dwordx4 v[218:221], v[238:239], off
	s_waitcnt vmcnt(7)
	v_pk_add_f32 v[18:19], v[224:225], v[18:19]
	v_pk_add_f32 v[16:17], v[222:223], v[16:17]
	global_load_dwordx4 v[222:225], v[240:241], off
	s_waitcnt vmcnt(7)
	v_pk_add_f32 v[14:15], v[148:149], v[14:15]
	v_pk_add_f32 v[12:13], v[146:147], v[12:13]
	global_load_dwordx4 v[146:149], v[226:227], off offset:1024
	s_waitcnt vmcnt(7)
	v_pk_add_f32 v[14:15], v[152:153], v[14:15]
	v_pk_add_f32 v[12:13], v[150:151], v[12:13]
	global_load_dwordx4 v[150:153], v[228:229], off offset:1024
	s_waitcnt vmcnt(7)
	v_pk_add_f32 v[14:15], v[156:157], v[14:15]
	v_pk_add_f32 v[12:13], v[154:155], v[12:13]
	global_load_dwordx4 v[154:157], v[230:231], off offset:1024
	s_waitcnt vmcnt(7)
	v_pk_add_f32 v[14:15], v[208:209], v[14:15]
	v_pk_add_f32 v[12:13], v[206:207], v[12:13]
	global_load_dwordx4 v[206:209], v[232:233], off offset:1024
	s_waitcnt vmcnt(7)
	v_pk_add_f32 v[14:15], v[212:213], v[14:15]
	v_pk_add_f32 v[12:13], v[210:211], v[12:13]
	global_load_dwordx4 v[210:213], v[234:235], off offset:1024
	s_waitcnt vmcnt(7)
	v_pk_add_f32 v[14:15], v[216:217], v[14:15]
	v_pk_add_f32 v[12:13], v[214:215], v[12:13]
	global_load_dwordx4 v[214:217], v[236:237], off offset:1024
	s_waitcnt vmcnt(7)
	v_pk_add_f32 v[14:15], v[220:221], v[14:15]
	v_pk_add_f32 v[12:13], v[218:219], v[12:13]
	global_load_dwordx4 v[218:221], v[238:239], off offset:1024
	s_waitcnt vmcnt(7)
	v_pk_add_f32 v[14:15], v[224:225], v[14:15]
	v_pk_add_f32 v[12:13], v[222:223], v[12:13]
	global_load_dwordx4 v[222:225], v[240:241], off offset:1024
	s_waitcnt vmcnt(7)
	v_pk_add_f32 v[10:11], v[148:149], v[10:11]
	v_pk_add_f32 v[8:9], v[146:147], v[8:9]
	global_load_dwordx4 v[146:149], v[226:227], off offset:2048
	s_waitcnt vmcnt(7)
	v_pk_add_f32 v[10:11], v[152:153], v[10:11]
	v_pk_add_f32 v[8:9], v[150:151], v[8:9]
	global_load_dwordx4 v[150:153], v[228:229], off offset:2048
	s_waitcnt vmcnt(7)
	v_pk_add_f32 v[10:11], v[156:157], v[10:11]
	v_pk_add_f32 v[8:9], v[154:155], v[8:9]
	global_load_dwordx4 v[154:157], v[230:231], off offset:2048
	s_waitcnt vmcnt(7)
	v_pk_add_f32 v[10:11], v[208:209], v[10:11]
	v_pk_add_f32 v[8:9], v[206:207], v[8:9]
	global_load_dwordx4 v[206:209], v[232:233], off offset:2048
	s_waitcnt vmcnt(7)
	v_pk_add_f32 v[10:11], v[212:213], v[10:11]
	v_pk_add_f32 v[8:9], v[210:211], v[8:9]
	global_load_dwordx4 v[210:213], v[234:235], off offset:2048
	s_waitcnt vmcnt(7)
	v_pk_add_f32 v[10:11], v[216:217], v[10:11]
	v_pk_add_f32 v[8:9], v[214:215], v[8:9]
	global_load_dwordx4 v[214:217], v[236:237], off offset:2048
	s_waitcnt vmcnt(7)
	v_pk_add_f32 v[10:11], v[220:221], v[10:11]
	v_pk_add_f32 v[8:9], v[218:219], v[8:9]
	global_load_dwordx4 v[218:221], v[238:239], off offset:2048
	s_waitcnt vmcnt(7)
	v_pk_add_f32 v[10:11], v[224:225], v[10:11]
	v_pk_add_f32 v[8:9], v[222:223], v[8:9]
	global_load_dwordx4 v[222:225], v[240:241], off offset:2048
	s_waitcnt vmcnt(7)
	v_pk_add_f32 v[2:3], v[148:149], v[2:3]
	v_pk_add_f32 v[0:1], v[146:147], v[0:1]
	global_load_dwordx4 v[146:149], v[226:227], off offset:3072
	s_waitcnt vmcnt(7)
	v_pk_add_f32 v[2:3], v[152:153], v[2:3]
	v_pk_add_f32 v[0:1], v[150:151], v[0:1]
	global_load_dwordx4 v[150:153], v[228:229], off offset:3072
	s_waitcnt vmcnt(7)
	v_pk_add_f32 v[2:3], v[156:157], v[2:3]
	v_pk_add_f32 v[0:1], v[154:155], v[0:1]
	global_load_dwordx4 v[154:157], v[230:231], off offset:3072
	s_waitcnt vmcnt(7)
	v_pk_add_f32 v[2:3], v[208:209], v[2:3]
	v_pk_add_f32 v[0:1], v[206:207], v[0:1]
	global_load_dwordx4 v[206:209], v[232:233], off offset:3072
	s_waitcnt vmcnt(7)
	v_pk_add_f32 v[2:3], v[212:213], v[2:3]
	v_pk_add_f32 v[0:1], v[210:211], v[0:1]
	global_load_dwordx4 v[210:213], v[234:235], off offset:3072
	s_waitcnt vmcnt(7)
	v_pk_add_f32 v[2:3], v[216:217], v[2:3]
	v_pk_add_f32 v[0:1], v[214:215], v[0:1]
	global_load_dwordx4 v[214:217], v[236:237], off offset:3072
	s_waitcnt vmcnt(7)
	v_pk_add_f32 v[2:3], v[220:221], v[2:3]
	v_pk_add_f32 v[0:1], v[218:219], v[0:1]
	global_load_dwordx4 v[218:221], v[238:239], off offset:3072
	s_waitcnt vmcnt(7)
	v_pk_add_f32 v[2:3], v[224:225], v[2:3]
	v_pk_add_f32 v[0:1], v[222:223], v[0:1]
	global_load_dwordx4 v[222:225], v[240:241], off offset:3072
	s_waitcnt vmcnt(7)
	v_pk_add_f32 v[6:7], v[148:149], v[6:7]
	v_pk_add_f32 v[4:5], v[146:147], v[4:5]
	s_waitcnt vmcnt(6)
	v_pk_add_f32 v[6:7], v[152:153], v[6:7]
	v_pk_add_f32 v[4:5], v[150:151], v[4:5]
	s_waitcnt vmcnt(5)
	v_pk_add_f32 v[6:7], v[156:157], v[6:7]
	v_pk_add_f32 v[4:5], v[154:155], v[4:5]
	s_waitcnt vmcnt(4)
	v_pk_add_f32 v[6:7], v[208:209], v[6:7]
	v_pk_add_f32 v[4:5], v[206:207], v[4:5]
	s_waitcnt vmcnt(3)
	v_pk_add_f32 v[6:7], v[212:213], v[6:7]
	v_pk_add_f32 v[4:5], v[210:211], v[4:5]
	s_waitcnt vmcnt(2)
	v_pk_add_f32 v[6:7], v[216:217], v[6:7]
	v_pk_add_f32 v[4:5], v[214:215], v[4:5]
	s_waitcnt vmcnt(1)
	v_pk_add_f32 v[6:7], v[220:221], v[6:7]
	v_pk_add_f32 v[4:5], v[218:219], v[4:5]
	s_waitcnt vmcnt(0)
	v_pk_add_f32 v[6:7], v[224:225], v[6:7]
	v_pk_add_f32 v[4:5], v[222:223], v[4:5]
	v_lshl_add_u64 v[128:129], v[196:197], 0, s[16:17]
	global_store_dwordx4 v[128:129], v[28:31], off
	global_store_dwordx4 v[128:129], v[24:27], off offset:1024
	global_store_dwordx4 v[128:129], v[20:23], off offset:2048
	global_store_dwordx4 v[128:129], v[16:19], off offset:3072
	v_add_co_u32_e32 v128, vcc, 0x1000, v128
	s_nop 1
	v_addc_co_u32_e32 v129, vcc, 0, v129, vcc
	global_store_dwordx4 v[128:129], v[12:15], off
	global_store_dwordx4 v[128:129], v[8:11], off offset:1024
	global_store_dwordx4 v[128:129], v[0:3], off offset:2048
	global_store_dwordx4 v[128:129], v[4:7], off offset:3072
